# S5 output epilogue: second token half moved to the idle lanes (permlane16 swap), 16 gelu evaluations per lane instead of 32 on half the lanes; scalar base + lane offset addressing
# speedup vs baseline: 1.0082x; 1.0055x over previous
.LBB0_652:
	s_mov_b64 s[2:3], exec
	v_readlane_b32 s36, v253, 51
	v_readlane_b32 s48, v253, 63
	v_readlane_b32 s49, v254, 0
	v_readlane_b32 s38, v253, 53
	v_readlane_b32 s39, v253, 54
	v_readlane_b32 s40, v253, 55
	v_readlane_b32 s41, v253, 56
	s_mov_b32 s41, 0xffff
	s_movk_i32 s40, 0x1fff
	s_movk_i32 s39, 0x4200
	v_readlane_b32 s38, v253, 49
	v_readlane_b32 s37, v253, 52
	v_readlane_b32 s42, v253, 57
	v_readlane_b32 s43, v253, 58
	v_readlane_b32 s44, v253, 59
	v_readlane_b32 s45, v253, 60
	v_readlane_b32 s46, v253, 61
	v_readlane_b32 s47, v253, 62
	v_readlane_b32 s50, v254, 1
	v_readlane_b32 s51, v254, 2
	v_and_b32_e32 v32, 15, v104
	v_lshrrev_b32_e32 v33, 4, v104
	v_or3_b32 v112, v198, s19, v32
	v_lshl_add_u64 v[34:35], v[112:113], 2, s[48:49]
	global_load_dword v96, v[34:35], off
	v_lshlrev_b32_e32 v36, 2, v196
	v_lshl_add_u32 v36, v33, 5, v36
	v_mul_u32_u24_e32 v36, 0x3800, v36
	v_lshl_add_u32 v36, v32, 1, v36
	v_readfirstlane_b32 s4, v106
	v_readfirstlane_b32 s5, v107
	v_mov_b32_e32 v40, v36
	v_add_u32_e32 v41, 0x3800, v36
	v_add_u32_e32 v42, 0x7000, v36
	v_add_u32_e32 v43, 0xa800, v36
	v_add_u32_e32 v44, 0x1c000, v36
	v_add_u32_e32 v45, 0x1f800, v36
	v_add_u32_e32 v46, 0x23000, v36
	v_add_u32_e32 v47, 0x26800, v36
	v_add_u32_e32 v48, 0x38000, v36
	v_add_u32_e32 v49, 0x3b800, v36
	v_add_u32_e32 v50, 0x3f000, v36
	v_add_u32_e32 v51, 0x42800, v36
	v_add_u32_e32 v52, 0x54000, v36
	v_add_u32_e32 v53, 0x57800, v36
	v_add_u32_e32 v54, 0x5b000, v36
	v_add_u32_e32 v55, 0x5e800, v36
	v_permlane16_swap_b32_e32 v0, v16
	v_permlane16_swap_b32_e32 v1, v17
	v_permlane16_swap_b32_e32 v2, v18
	v_permlane16_swap_b32_e32 v3, v19
	v_permlane16_swap_b32_e32 v4, v20
	v_permlane16_swap_b32_e32 v5, v21
	v_permlane16_swap_b32_e32 v6, v22
	v_permlane16_swap_b32_e32 v7, v23
	v_permlane16_swap_b32_e32 v8, v24
	v_permlane16_swap_b32_e32 v9, v25
	v_permlane16_swap_b32_e32 v10, v26
	v_permlane16_swap_b32_e32 v11, v27
	v_permlane16_swap_b32_e32 v12, v28
	v_permlane16_swap_b32_e32 v13, v29
	v_permlane16_swap_b32_e32 v14, v30
	v_permlane16_swap_b32_e32 v15, v31
	global_load_ushort v56, v40, s[4:5]
	global_load_ushort v57, v41, s[4:5]
	global_load_ushort v58, v42, s[4:5]
	global_load_ushort v59, v43, s[4:5]
	global_load_ushort v60, v44, s[4:5]
	global_load_ushort v61, v45, s[4:5]
	global_load_ushort v62, v46, s[4:5]
	global_load_ushort v63, v47, s[4:5]
	global_load_ushort v64, v48, s[4:5]
	global_load_ushort v65, v49, s[4:5]
	global_load_ushort v66, v50, s[4:5]
	global_load_ushort v67, v51, s[4:5]
	global_load_ushort v68, v52, s[4:5]
	global_load_ushort v69, v53, s[4:5]
	global_load_ushort v70, v54, s[4:5]
	global_load_ushort v71, v55, s[4:5]
	s_waitcnt vmcnt(0)
	v_lshlrev_b32_e32 v56, 16, v56
	v_lshlrev_b32_e32 v57, 16, v57
	v_fmac_f32_e32 v0, v96, v56
	v_fmac_f32_e32 v1, v96, v57
	v_mul_f32_e32 v72, 0x3d372713, v0
	v_mul_f32_e32 v73, 0x3d372713, v1
	v_mul_f32_e32 v72, v0, v72
	v_mul_f32_e32 v73, v1, v73
	v_fma_f32 v72, v0, v72, v0
	v_fma_f32 v73, v1, v73, v1
	v_mul_f32_e32 v72, 0x3f4c422a, v72
	v_mul_f32_e32 v73, 0x3f4c422a, v73
	v_mul_f32_e32 v72, -2.0, v72
	v_mul_f32_e32 v73, -2.0, v73
	v_mul_f32_e32 v72, 0x3fb8aa3b, v72
	v_mul_f32_e32 v73, 0x3fb8aa3b, v73
	v_exp_f32_e32 v72, v72
	v_exp_f32_e32 v73, v73
	v_add_f32_e32 v72, 1.0, v72
	v_add_f32_e32 v73, 1.0, v73
	v_rcp_f32_e32 v72, v72
	v_rcp_f32_e32 v73, v73
	v_mul_f32_e32 v0, v0, v72
	v_mul_f32_e32 v1, v1, v73
	v_bfe_u32 v72, v0, 16, 1
	v_bfe_u32 v73, v1, 16, 1
	v_add3_u32 v0, v0, v72, s33
	v_add3_u32 v1, v1, v73, s33
	global_store_short_d16_hi v40, v0, s[4:5]
	global_store_short_d16_hi v41, v1, s[4:5]
	v_lshlrev_b32_e32 v58, 16, v58
	v_lshlrev_b32_e32 v59, 16, v59
	v_fmac_f32_e32 v2, v96, v58
	v_fmac_f32_e32 v3, v96, v59
	v_mul_f32_e32 v72, 0x3d372713, v2
	v_mul_f32_e32 v73, 0x3d372713, v3
	v_mul_f32_e32 v72, v2, v72
	v_mul_f32_e32 v73, v3, v73
	v_fma_f32 v72, v2, v72, v2
	v_fma_f32 v73, v3, v73, v3
	v_mul_f32_e32 v72, 0x3f4c422a, v72
	v_mul_f32_e32 v73, 0x3f4c422a, v73
	v_mul_f32_e32 v72, -2.0, v72
	v_mul_f32_e32 v73, -2.0, v73
	v_mul_f32_e32 v72, 0x3fb8aa3b, v72
	v_mul_f32_e32 v73, 0x3fb8aa3b, v73
	v_exp_f32_e32 v72, v72
	v_exp_f32_e32 v73, v73
	v_add_f32_e32 v72, 1.0, v72
	v_add_f32_e32 v73, 1.0, v73
	v_rcp_f32_e32 v72, v72
	v_rcp_f32_e32 v73, v73
	v_mul_f32_e32 v2, v2, v72
	v_mul_f32_e32 v3, v3, v73
	v_bfe_u32 v72, v2, 16, 1
	v_bfe_u32 v73, v3, 16, 1
	v_add3_u32 v2, v2, v72, s33
	v_add3_u32 v3, v3, v73, s33
	global_store_short_d16_hi v42, v2, s[4:5]
	global_store_short_d16_hi v43, v3, s[4:5]
	v_lshlrev_b32_e32 v60, 16, v60
	v_lshlrev_b32_e32 v61, 16, v61
	v_fmac_f32_e32 v4, v96, v60
	v_fmac_f32_e32 v5, v96, v61
	v_mul_f32_e32 v72, 0x3d372713, v4
	v_mul_f32_e32 v73, 0x3d372713, v5
	v_mul_f32_e32 v72, v4, v72
	v_mul_f32_e32 v73, v5, v73
	v_fma_f32 v72, v4, v72, v4
	v_fma_f32 v73, v5, v73, v5
	v_mul_f32_e32 v72, 0x3f4c422a, v72
	v_mul_f32_e32 v73, 0x3f4c422a, v73
	v_mul_f32_e32 v72, -2.0, v72
	v_mul_f32_e32 v73, -2.0, v73
	v_mul_f32_e32 v72, 0x3fb8aa3b, v72
	v_mul_f32_e32 v73, 0x3fb8aa3b, v73
	v_exp_f32_e32 v72, v72
	v_exp_f32_e32 v73, v73
	v_add_f32_e32 v72, 1.0, v72
	v_add_f32_e32 v73, 1.0, v73
	v_rcp_f32_e32 v72, v72
	v_rcp_f32_e32 v73, v73
	v_mul_f32_e32 v4, v4, v72
	v_mul_f32_e32 v5, v5, v73
	v_bfe_u32 v72, v4, 16, 1
	v_bfe_u32 v73, v5, 16, 1
	v_add3_u32 v4, v4, v72, s33
	v_add3_u32 v5, v5, v73, s33
	global_store_short_d16_hi v44, v4, s[4:5]
	global_store_short_d16_hi v45, v5, s[4:5]
	v_lshlrev_b32_e32 v62, 16, v62
	v_lshlrev_b32_e32 v63, 16, v63
	v_fmac_f32_e32 v6, v96, v62
	v_fmac_f32_e32 v7, v96, v63
	v_mul_f32_e32 v72, 0x3d372713, v6
	v_mul_f32_e32 v73, 0x3d372713, v7
	v_mul_f32_e32 v72, v6, v72
	v_mul_f32_e32 v73, v7, v73
	v_fma_f32 v72, v6, v72, v6
	v_fma_f32 v73, v7, v73, v7
	v_mul_f32_e32 v72, 0x3f4c422a, v72
	v_mul_f32_e32 v73, 0x3f4c422a, v73
	v_mul_f32_e32 v72, -2.0, v72
	v_mul_f32_e32 v73, -2.0, v73
	v_mul_f32_e32 v72, 0x3fb8aa3b, v72
	v_mul_f32_e32 v73, 0x3fb8aa3b, v73
	v_exp_f32_e32 v72, v72
	v_exp_f32_e32 v73, v73
	v_add_f32_e32 v72, 1.0, v72
	v_add_f32_e32 v73, 1.0, v73
	v_rcp_f32_e32 v72, v72
	v_rcp_f32_e32 v73, v73
	v_mul_f32_e32 v6, v6, v72
	v_mul_f32_e32 v7, v7, v73
	v_bfe_u32 v72, v6, 16, 1
	v_bfe_u32 v73, v7, 16, 1
	v_add3_u32 v6, v6, v72, s33
	v_add3_u32 v7, v7, v73, s33
	global_store_short_d16_hi v46, v6, s[4:5]
	global_store_short_d16_hi v47, v7, s[4:5]
	v_lshlrev_b32_e32 v64, 16, v64
	v_lshlrev_b32_e32 v65, 16, v65
	v_fmac_f32_e32 v8, v96, v64
	v_fmac_f32_e32 v9, v96, v65
	v_mul_f32_e32 v72, 0x3d372713, v8
	v_mul_f32_e32 v73, 0x3d372713, v9
	v_mul_f32_e32 v72, v8, v72
	v_mul_f32_e32 v73, v9, v73
	v_fma_f32 v72, v8, v72, v8
	v_fma_f32 v73, v9, v73, v9
	v_mul_f32_e32 v72, 0x3f4c422a, v72
	v_mul_f32_e32 v73, 0x3f4c422a, v73
	v_mul_f32_e32 v72, -2.0, v72
	v_mul_f32_e32 v73, -2.0, v73
	v_mul_f32_e32 v72, 0x3fb8aa3b, v72
	v_mul_f32_e32 v73, 0x3fb8aa3b, v73
	v_exp_f32_e32 v72, v72
	v_exp_f32_e32 v73, v73
	v_add_f32_e32 v72, 1.0, v72
	v_add_f32_e32 v73, 1.0, v73
	v_rcp_f32_e32 v72, v72
	v_rcp_f32_e32 v73, v73
	v_mul_f32_e32 v8, v8, v72
	v_mul_f32_e32 v9, v9, v73
	v_bfe_u32 v72, v8, 16, 1
	v_bfe_u32 v73, v9, 16, 1
	v_add3_u32 v8, v8, v72, s33
	v_add3_u32 v9, v9, v73, s33
	global_store_short_d16_hi v48, v8, s[4:5]
	global_store_short_d16_hi v49, v9, s[4:5]
	v_lshlrev_b32_e32 v66, 16, v66
	v_lshlrev_b32_e32 v67, 16, v67
	v_fmac_f32_e32 v10, v96, v66
	v_fmac_f32_e32 v11, v96, v67
	v_mul_f32_e32 v72, 0x3d372713, v10
	v_mul_f32_e32 v73, 0x3d372713, v11
	v_mul_f32_e32 v72, v10, v72
	v_mul_f32_e32 v73, v11, v73
	v_fma_f32 v72, v10, v72, v10
	v_fma_f32 v73, v11, v73, v11
	v_mul_f32_e32 v72, 0x3f4c422a, v72
	v_mul_f32_e32 v73, 0x3f4c422a, v73
	v_mul_f32_e32 v72, -2.0, v72
	v_mul_f32_e32 v73, -2.0, v73
	v_mul_f32_e32 v72, 0x3fb8aa3b, v72
	v_mul_f32_e32 v73, 0x3fb8aa3b, v73
	v_exp_f32_e32 v72, v72
	v_exp_f32_e32 v73, v73
	v_add_f32_e32 v72, 1.0, v72
	v_add_f32_e32 v73, 1.0, v73
	v_rcp_f32_e32 v72, v72
	v_rcp_f32_e32 v73, v73
	v_mul_f32_e32 v10, v10, v72
	v_mul_f32_e32 v11, v11, v73
	v_bfe_u32 v72, v10, 16, 1
	v_bfe_u32 v73, v11, 16, 1
	v_add3_u32 v10, v10, v72, s33
	v_add3_u32 v11, v11, v73, s33
	global_store_short_d16_hi v50, v10, s[4:5]
	global_store_short_d16_hi v51, v11, s[4:5]
	v_lshlrev_b32_e32 v68, 16, v68
	v_lshlrev_b32_e32 v69, 16, v69
	v_fmac_f32_e32 v12, v96, v68
	v_fmac_f32_e32 v13, v96, v69
	v_mul_f32_e32 v72, 0x3d372713, v12
	v_mul_f32_e32 v73, 0x3d372713, v13
	v_mul_f32_e32 v72, v12, v72
	v_mul_f32_e32 v73, v13, v73
	v_fma_f32 v72, v12, v72, v12
	v_fma_f32 v73, v13, v73, v13
	v_mul_f32_e32 v72, 0x3f4c422a, v72
	v_mul_f32_e32 v73, 0x3f4c422a, v73
	v_mul_f32_e32 v72, -2.0, v72
	v_mul_f32_e32 v73, -2.0, v73
	v_mul_f32_e32 v72, 0x3fb8aa3b, v72
	v_mul_f32_e32 v73, 0x3fb8aa3b, v73
	v_exp_f32_e32 v72, v72
	v_exp_f32_e32 v73, v73
	v_add_f32_e32 v72, 1.0, v72
	v_add_f32_e32 v73, 1.0, v73
	v_rcp_f32_e32 v72, v72
	v_rcp_f32_e32 v73, v73
	v_mul_f32_e32 v12, v12, v72
	v_mul_f32_e32 v13, v13, v73
	v_bfe_u32 v72, v12, 16, 1
	v_bfe_u32 v73, v13, 16, 1
	v_add3_u32 v12, v12, v72, s33
	v_add3_u32 v13, v13, v73, s33
	global_store_short_d16_hi v52, v12, s[4:5]
	global_store_short_d16_hi v53, v13, s[4:5]
	v_lshlrev_b32_e32 v70, 16, v70
	v_lshlrev_b32_e32 v71, 16, v71
	v_fmac_f32_e32 v14, v96, v70
	v_fmac_f32_e32 v15, v96, v71
	v_mul_f32_e32 v72, 0x3d372713, v14
	v_mul_f32_e32 v73, 0x3d372713, v15
	v_mul_f32_e32 v72, v14, v72
	v_mul_f32_e32 v73, v15, v73
	v_fma_f32 v72, v14, v72, v14
	v_fma_f32 v73, v15, v73, v15
	v_mul_f32_e32 v72, 0x3f4c422a, v72
	v_mul_f32_e32 v73, 0x3f4c422a, v73
	v_mul_f32_e32 v72, -2.0, v72
	v_mul_f32_e32 v73, -2.0, v73
	v_mul_f32_e32 v72, 0x3fb8aa3b, v72
	v_mul_f32_e32 v73, 0x3fb8aa3b, v73
	v_exp_f32_e32 v72, v72
	v_exp_f32_e32 v73, v73
	v_add_f32_e32 v72, 1.0, v72
	v_add_f32_e32 v73, 1.0, v73
	v_rcp_f32_e32 v72, v72
	v_rcp_f32_e32 v73, v73
	v_mul_f32_e32 v14, v14, v72
	v_mul_f32_e32 v15, v15, v73
	v_bfe_u32 v72, v14, 16, 1
	v_bfe_u32 v73, v15, 16, 1
	v_add3_u32 v14, v14, v72, s33
	v_add3_u32 v15, v15, v73, s33
	global_store_short_d16_hi v54, v14, s[4:5]
	global_store_short_d16_hi v55, v15, s[4:5]
	s_branch .LBB0_639
